# hgrn pass 2: MIX stores as global_store left in flight across the chunk loop top (vmcnt(2))
# speedup vs baseline: 1.0409x; 1.0051x over previous
; template <bool FULL>
; DI void hgrn_pass(const Params& p, const int j, char* lds) {
;     ...
;         const size_t rowS = (size_t)b * SEQ + seg * 256;
;         float segsum = 0.f;
;         float lf[16]; u32x4 kq[2], qq[2], vv[2];
;     ...
;         H_LOADS(0);
.LBB0_188:
	s_or_b64 exec, exec, s[64:65]
	v_ashrrev_i32_e32 v82, 6, v80
	v_ashrrev_i32_e32 v83, 31, v82
	v_lshlrev_b32_e32 v32, 4, v80
	v_lshlrev_b64 v[84:85], 11, v[82:83]
	v_and_b32_e32 v90, 0x380, v32
	v_lshl_or_b32 v92, v81, 8, v84
	v_lshlrev_b32_e32 v32, 2, v90
	v_lshl_add_u64 v[34:35], v[134:135], 0, v[32:33]
	v_or_b32_e32 v84, v92, v132
	v_or_b32_e32 v32, 1, v132
	v_lshlrev_b64 v[36:37], 12, v[84:85]
	v_or_b32_e32 v84, v92, v32
	v_or_b32_e32 v32, 2, v132
	v_lshlrev_b64 v[38:39], 12, v[84:85]
	v_or_b32_e32 v84, v92, v32
	v_or_b32_e32 v32, 3, v132
	v_lshlrev_b64 v[40:41], 12, v[84:85]
	v_or_b32_e32 v84, v92, v32
	v_or_b32_e32 v32, 4, v132
	v_lshlrev_b64 v[42:43], 12, v[84:85]
	v_or_b32_e32 v84, v92, v32
	v_or_b32_e32 v32, 5, v132
	v_lshlrev_b64 v[44:45], 12, v[84:85]
	v_or_b32_e32 v84, v92, v32
	v_or_b32_e32 v32, 6, v132
	v_lshlrev_b64 v[46:47], 12, v[84:85]
	v_or_b32_e32 v84, v92, v32
	v_or_b32_e32 v32, 7, v132
	v_lshlrev_b64 v[86:87], 12, v[84:85]
	v_or_b32_e32 v84, v92, v32
	v_or_b32_e32 v32, 8, v132
	v_lshl_add_u64 v[36:37], v[34:35], 0, v[36:37]
	v_lshlrev_b64 v[88:89], 12, v[84:85]
	v_or_b32_e32 v84, v92, v32
	v_or_b32_e32 v32, 9, v132
	v_lshl_add_u64 v[38:39], v[34:35], 0, v[38:39]
	v_lshl_add_u64 v[40:41], v[34:35], 0, v[40:41]
	v_lshl_add_u64 v[42:43], v[34:35], 0, v[42:43]
	v_lshl_add_u64 v[44:45], v[34:35], 0, v[44:45]
	v_lshl_add_u64 v[46:47], v[34:35], 0, v[46:47]
	v_lshl_add_u64 v[86:87], v[34:35], 0, v[86:87]
	v_lshl_add_u64 v[88:89], v[34:35], 0, v[88:89]
	flat_load_dword v214, v[36:37]
	flat_load_dword v215, v[38:39]
	flat_load_dword v216, v[40:41]
	flat_load_dword v217, v[42:43]
	flat_load_dword v218, v[44:45]
	flat_load_dword v219, v[46:47]
	flat_load_dword v220, v[86:87]
	flat_load_dword v221, v[88:89]
	v_lshlrev_b64 v[36:37], 12, v[84:85]
	v_or_b32_e32 v84, v92, v32
	v_or_b32_e32 v32, 10, v132
	v_lshlrev_b64 v[38:39], 12, v[84:85]
	v_or_b32_e32 v84, v92, v32
	v_lshlrev_b64 v[40:41], 12, v[84:85]
	v_or_b32_e32 v84, v92, v142
	v_lshlrev_b64 v[42:43], 12, v[84:85]
	v_or_b32_e32 v84, v92, v144
	v_lshlrev_b64 v[44:45], 12, v[84:85]
	v_or_b32_e32 v84, v92, v146
	v_lshlrev_b64 v[46:47], 12, v[84:85]
	v_or_b32_e32 v84, v92, v148
	v_lshlrev_b64 v[86:87], 12, v[84:85]
	v_or_b32_e32 v84, v92, v150
	v_lshl_add_u64 v[36:37], v[34:35], 0, v[36:37]
	v_lshl_add_u64 v[42:43], v[34:35], 0, v[42:43]
	v_lshl_add_u64 v[44:45], v[34:35], 0, v[44:45]
	v_lshlrev_b64 v[88:89], 12, v[84:85]
	v_lshl_add_u64 v[38:39], v[34:35], 0, v[38:39]
	v_lshl_add_u64 v[40:41], v[34:35], 0, v[40:41]
	v_lshl_add_u64 v[46:47], v[34:35], 0, v[46:47]
	v_lshl_add_u64 v[86:87], v[34:35], 0, v[86:87]
	v_lshl_add_u64 v[34:35], v[34:35], 0, v[88:89]
	flat_load_dword v222, v[36:37]
	flat_load_dword v223, v[38:39]
	flat_load_dword v224, v[40:41]
	flat_load_dword v225, v[42:43]
	flat_load_dword v226, v[44:45]
	flat_load_dword v227, v[46:47]
	flat_load_dword v228, v[86:87]
	flat_load_dword v229, v[34:35]
	v_or_b32_e32 v32, v92, v152
	v_mov_b64_e32 v[42:43], s[86:87]
	v_or_b32_e32 v44, v92, v154
	v_mad_u64_u32 v[34:35], s[64:65], v32, s77, v[42:43]
	v_mad_u64_u32 v[42:43], s[64:65], v44, s77, v[42:43]
	v_mad_i32_i24 v35, v85, s77, v35
	v_lshlrev_b32_e32 v32, 1, v90
	v_mad_i32_i24 v43, v85, s77, v43
	v_lshl_or_b32 v84, v82, 10, v90
	v_lshl_add_u64 v[34:35], v[34:35], 0, v[32:33]
	v_mov_b32_e32 v171, v33
	v_lshl_add_u64 v[42:43], v[42:43], 0, v[32:33]
	v_or_b32_e32 v86, v84, v157
	v_lshl_add_u64 v[38:39], v[34:35], 0, v[170:171]
	v_lshl_add_u64 v[46:47], v[42:43], 0, v[170:171]
	v_lshlrev_b32_e32 v32, 9, v81
	v_ashrrev_i32_e32 v87, 31, v86
	v_or_b32_e32 v90, v84, v159
	flat_load_dwordx4 v[34:37], v[38:39] offset:2048
	s_nop 0
	flat_load_dwordx4 v[38:41], v[38:39]
	s_nop 0
	flat_load_dwordx4 v[42:45], v[46:47] offset:2048
	flat_load_dwordx4 v[96:99], v[46:47]
	v_lshl_add_u64 v[46:47], v[136:137], 0, v[32:33]
	v_lshlrev_b64 v[86:87], 12, v[86:87]
	v_ashrrev_i32_e32 v91, 31, v90
	v_lshl_add_u64 v[88:89], v[46:47], 0, v[86:87]
	v_lshlrev_b64 v[90:91], 12, v[90:91]
	v_lshl_add_u64 v[46:47], v[46:47], 0, v[90:91]
	flat_load_dwordx4 v[100:103], v[88:89]
	flat_load_dwordx4 v[104:107], v[46:47]
	v_lshl_add_u64 v[46:47], v[160:161], 0, v[90:91]
	v_lshl_add_u64 v[86:87], v[160:161], 0, v[86:87]
	s_mov_b32 s67, 0xc00000
	v_lshl_add_u64 v[46:47], v[46:47], 0, v[32:33]
	v_lshl_add_u64 v[172:173], v[86:87], 0, v[32:33]
	v_mad_i64_i32 v[86:87], s[64:65], v82, s67, v[162:163]
	s_mov_b32 vcc_lo, 0x180000
	v_lshlrev_b32_e32 v32, 5, v80
	v_mad_u64_u32 v[86:87], s[64:65], v81, vcc_lo, v[86:87]
	v_and_b32_e32 v32, 0x700, v32
	v_lshl_add_u64 v[174:175], v[86:87], 0, v[32:33]
	v_mad_i64_i32 v[86:87], s[64:65], v82, s67, v[164:165]
	v_lshlrev_b64 v[82:83], 23, v[82:83]
	v_or_b32_e32 v82, v166, v82
	v_lshlrev_b32_e32 v80, 6, v80
	v_or_b32_e32 v84, v92, v138
	v_mad_u64_u32 v[86:87], s[64:65], v81, vcc_lo, v[86:87]
	v_lshl_or_b32 v82, v81, 20, v82
	v_and_b32_e32 v80, 0xe00, v80
	v_mov_b32_e32 v81, v33
	v_lshlrev_b64 v[180:181], 11, v[84:85]
	v_lshl_add_u64 v[178:179], v[82:83], 0, v[80:81]
	v_or_b32_e32 v80, v168, v180
	v_or_b32_e32 v180, v80, v32
	v_mad_u64_u32 v[80:81], s[64:65], v84, s77, 0
	v_or_b32_e32 v80, v168, v80
	s_mov_b32 s66, 7
	v_lshl_add_u64 v[176:177], v[86:87], 0, v[32:33]
	v_mad_i32_i24 v183, v85, s77, v81
	v_or_b32_e32 v182, v80, v32
	s_waitcnt vmcnt(0)
	s_branch .LBB0_190
; #define MFMA32(a, b, c) __builtin_amdgcn_mfma_f32_32x32x16_bf16((a), (b), (c), 0, 0, 0)
; DI int crow(int i, int h) { return (i & 3) + 8 * (i >> 2) + 4 * h; }
; template <bool FULL>
; DI void hgrn_pass(const Params& p, const int j, char* lds) {
;     ...
;             if (FULL) {
;                 f32x16 at;
; #pragma unroll
;                 for (int i = 0; i < 16; ++i) at[i] = 0.f;
; #pragma unroll
;                 for (int ks = 0; ks < 8; ++ks) { const bf16x8 a = *(const bf16x8*)(Kt + l31 * LQ + ks * 16 + 8 * hh); const bf16x8 bq = *(const bf16x8*)(Qh + l31 * LQ + ks * 16 + 8 * hh); at = MFMA32(a, bq, at); }
; #pragma unroll
;                 for (int i = 0; i < 16; ++i) at[i] = (crow(i, hh) <= l31) ? at[i] : 0.f;
; #pragma unroll
;                 for (int i = 0; i < 16; ++i) o[i] = 0.f;
; #pragma unroll
;                 for (int kt = 0; kt < 4; ++kt)
; #pragma unroll
;                     for (int s2 = 0; s2 < 2; ++s2) { const bf16_t* qp = Qh + l31 * LQ + 32 * kt + 16 * s2 + 4 * hh; const bf16x8 aq = ld_b64x2(qp, qp + 8); const bf16x8 bs = pack8(S[kt], s2); o = MFMA32(aq, bs, o); }
; #pragma unroll
;                 for (int s2 = 0; s2 < 2; ++s2) { const bf16_t* vp = VTs + (32 * w + l31) * LV + 16 * s2 + 4 * hh; const bf16x8 bv = ld_b64x2(vp, vp + 8); const bf16x8 pa = pack8(at, s2); o = MFMA32(pa, bv, o); }
.LBB0_189:
	s_waitcnt lgkmcnt(0)
	s_barrier
	ds_read_b128 v[80:83], v149 offset:27136
	ds_read_b128 v[84:87], v149 offset:18432
	ds_read_b128 v[116:119], v149 offset:18464
	ds_read_b128 v[120:123], v149 offset:27168
	s_waitcnt lgkmcnt(0)
	v_mfma_f32_32x32x16_bf16 v[80:95], v[80:83], v[84:87], 0
	v_add_u32_e32 v124, 0x4800, v207
	s_mov_b32 s64, 0x6681000
	s_add_i32 s66, s66, -1
	v_lshl_add_u64 v[46:47], v[46:47], 0, 64
	v_lshl_add_u64 v[172:173], v[172:173], 0, 64
	v_lshl_add_u64 v[174:175], v[174:175], 0, s[96:97]
	v_lshl_add_u64 v[176:177], v[176:177], 0, s[96:97]
	v_mfma_f32_32x32x16_bf16 v[80:95], v[120:123], v[116:119], v[80:95]
	ds_read_b128 v[116:119], v149 offset:27200
	ds_read_b128 v[120:123], v149 offset:18496
	v_lshl_add_u64 v[178:179], v[178:179], 0, s[0:1]
	v_lshl_add_u64 v[182:183], v[182:183], 0, s[96:97]
	s_cmp_eq_u32 s66, -1
	s_waitcnt lgkmcnt(0)
	v_mfma_f32_32x32x16_bf16 v[80:95], v[116:119], v[120:123], v[80:95]
	ds_read_b128 v[116:119], v149 offset:27232
	ds_read_b128 v[120:123], v149 offset:18528
	s_waitcnt lgkmcnt(0)
	v_mfma_f32_32x32x16_bf16 v[80:95], v[116:119], v[120:123], v[80:95]
	ds_read_b128 v[116:119], v149 offset:27264
	ds_read_b128 v[120:123], v149 offset:18560
	s_waitcnt lgkmcnt(0)
	v_mfma_f32_32x32x16_bf16 v[80:95], v[116:119], v[120:123], v[80:95]
	ds_read_b128 v[116:119], v149 offset:27296
	ds_read_b128 v[120:123], v149 offset:18592
	s_waitcnt lgkmcnt(0)
	v_mfma_f32_32x32x16_bf16 v[80:95], v[116:119], v[120:123], v[80:95]
	ds_read_b128 v[116:119], v149 offset:27328
	ds_read_b128 v[120:123], v149 offset:18624
	s_waitcnt lgkmcnt(0)
	v_mfma_f32_32x32x16_bf16 v[80:95], v[116:119], v[120:123], v[80:95]
	ds_read_b128 v[116:119], v149 offset:27360
	ds_read_b128 v[120:123], v149 offset:18656
	s_waitcnt lgkmcnt(0)
	v_mfma_f32_32x32x16_bf16 v[80:95], v[116:119], v[120:123], v[80:95]
	v_cvt_pk_bf16_f32 v120, v8, v9
	v_cvt_pk_bf16_f32 v121, v10, v11
	v_cvt_pk_bf16_f32 v122, v12, v13
	v_cvt_pk_bf16_f32 v123, v14, v15
	s_nop 7
	v_cndmask_b32_e64 v32, v80, 0, s[4:5]
	v_cndmask_b32_e64 v128, 0, v81, s[6:7]
	v_cndmask_b32_e64 v129, v82, 0, s[8:9]
	v_cndmask_b32_e64 v130, v83, 0, s[10:11]
	ds_read2_b64 v[80:83], v124 offset1:2
	ds_read2_b64 v[116:119], v124 offset0:4 offset1:6
	v_cndmask_b32_e64 v131, v84, 0, s[12:13]
	v_cndmask_b32_e64 v171, v85, 0, s[14:15]
	v_cndmask_b32_e64 v193, v86, 0, s[16:17]
	v_cndmask_b32_e64 v196, v87, 0, s[18:19]
	v_cvt_pk_bf16_f32 v84, v0, v1
	v_cvt_pk_bf16_f32 v85, v2, v3
	v_cvt_pk_bf16_f32 v86, v4, v5
	v_cvt_pk_bf16_f32 v87, v6, v7
	v_cndmask_b32_e64 v230, v88, 0, s[20:21]
	v_cndmask_b32_e64 v231, v89, 0, s[22:23]
	v_cndmask_b32_e64 v232, v90, 0, s[24:25]
	v_cndmask_b32_e64 v233, v91, 0, s[26:27]
	v_cndmask_b32_e64 v234, v92, 0, s[28:29]
	v_cndmask_b32_e64 v235, v93, 0, s[30:31]
	v_cndmask_b32_e64 v236, v94, 0, s[34:35]
	v_cndmask_b32_e64 v237, v95, 0, s[36:37]
	s_waitcnt lgkmcnt(0)
	v_mfma_f32_32x32x16_bf16 v[80:95], v[80:83], v[84:87], 0
	v_cvt_pk_bf16_f32 v128, v32, v128
	v_add_u32_e32 v32, v151, v147
	v_cvt_pk_bf16_f32 v129, v129, v130
	v_cvt_pk_bf16_f32 v130, v131, v171
	v_cvt_pk_bf16_f32 v131, v193, v196
	v_mfma_f32_32x32x16_bf16 v[80:95], v[116:119], v[120:123], v[80:95]
	ds_read2_b64 v[116:119], v124 offset0:8 offset1:10
	v_cvt_pk_bf16_f32 v120, v16, v17
	v_cvt_pk_bf16_f32 v121, v18, v19
	v_cvt_pk_bf16_f32 v122, v20, v21
	v_cvt_pk_bf16_f32 v123, v22, v23
	s_waitcnt lgkmcnt(0)
	s_nop 0
	v_mfma_f32_32x32x16_bf16 v[80:95], v[116:119], v[120:123], v[80:95]
	ds_read2_b64 v[116:119], v124 offset0:12 offset1:14
	v_cvt_pk_bf16_f32 v120, v24, v25
	v_cvt_pk_bf16_f32 v121, v26, v27
	v_cvt_pk_bf16_f32 v122, v28, v29
	v_cvt_pk_bf16_f32 v123, v30, v31
	s_waitcnt lgkmcnt(0)
	s_nop 0
	v_mfma_f32_32x32x16_bf16 v[80:95], v[116:119], v[120:123], v[80:95]
	ds_read2_b64 v[116:119], v124 offset0:16 offset1:18
	v_cvt_pk_bf16_f32 v120, v48, v49
	v_cvt_pk_bf16_f32 v121, v50, v51
	v_cvt_pk_bf16_f32 v122, v52, v53
	v_cvt_pk_bf16_f32 v123, v54, v55
	s_waitcnt lgkmcnt(0)
	s_nop 0
	v_mfma_f32_32x32x16_bf16 v[80:95], v[116:119], v[120:123], v[80:95]
	ds_read2_b64 v[116:119], v124 offset0:20 offset1:22
	v_cvt_pk_bf16_f32 v120, v56, v57
	v_cvt_pk_bf16_f32 v121, v58, v59
	v_cvt_pk_bf16_f32 v122, v60, v61
	v_cvt_pk_bf16_f32 v123, v62, v63
	s_waitcnt lgkmcnt(0)
	s_nop 0
	v_mfma_f32_32x32x16_bf16 v[80:95], v[116:119], v[120:123], v[80:95]
	ds_read2_b64 v[116:119], v124 offset0:24 offset1:26
	v_cvt_pk_bf16_f32 v120, v64, v65
	v_cvt_pk_bf16_f32 v121, v66, v67
	v_cvt_pk_bf16_f32 v122, v68, v69
	v_cvt_pk_bf16_f32 v123, v70, v71
	s_waitcnt lgkmcnt(0)
	s_nop 0
	v_mfma_f32_32x32x16_bf16 v[80:95], v[116:119], v[120:123], v[80:95]
	ds_read2_b64 v[116:119], v124 offset0:28 offset1:30
	v_cvt_pk_bf16_f32 v120, v72, v73
	v_cvt_pk_bf16_f32 v121, v74, v75
	v_cvt_pk_bf16_f32 v122, v76, v77
	v_cvt_pk_bf16_f32 v123, v78, v79
	s_waitcnt lgkmcnt(0)
	s_nop 0
	v_mfma_f32_32x32x16_bf16 v[80:95], v[116:119], v[120:123], v[80:95]
	v_add_u32_e32 v116, 0xb000, v151
	ds_read2_b64 v[124:127], v116 offset0:128 offset1:130
	ds_read2_b64 v[116:119], v116 offset0:132 offset1:134
	v_cvt_pk_bf16_f32 v120, v230, v231
	v_cvt_pk_bf16_f32 v121, v232, v233
	v_cvt_pk_bf16_f32 v122, v234, v235
	v_cvt_pk_bf16_f32 v123, v236, v237
	ds_read_b128 v[230:233], v153 offset:1024
	ds_read_b128 v[234:237], v153 offset:1056
	ds_read_b128 v[238:241], v153 offset:1088
	ds_read_b128 v[242:245], v153 offset:1120
	s_waitcnt lgkmcnt(0)
; #define MFMA32(a, b, c) __builtin_amdgcn_mfma_f32_32x32x16_bf16((a), (b), (c), 0, 0, 0)
; DI int crow(int i, int h) { return (i & 3) + 8 * (i >> 2) + 4 * h; }
; template <bool FULL>
; DI void hgrn_pass(const Params& p, const int j, char* lds) {
;     ...
;                 for (int s2 = 0; s2 < 2; ++s2) { const bf16_t* vp = VTs + (32 * w + l31) * LV + 16 * s2 + 4 * hh; const bf16x8 bv = ld_b64x2(vp, vp + 8); const bf16x8 pa = pack8(at, s2); o = MFMA32(pa, bv, o); }
;             }
; #pragma unroll
;             for (int kt = 0; kt < 4; ++kt) {
; #pragma unroll
;                 for (int g = 0; g < 4; ++g) { const f32x4 dv = *(const f32x4*)(dvec + 32 * kt + 8 * g + 4 * hh);
;                     S[kt][4 * g] *= dv[0]; S[kt][4 * g + 1] *= dv[1]; S[kt][4 * g + 2] *= dv[2]; S[kt][4 * g + 3] *= dv[3]; }
; #pragma unroll
;                 for (int s2 = 0; s2 < 2; ++s2) { const int kr_ = 32 * kt + l31; const bf16x8 a = *(const bf16x8*)(KhT + (kr_ ^ ((kr_ >> 3) & 7)) * LV + 16 * s2 + 8 * hh); const bf16x8 bv = *(const bf16x8*)(VTs + (32 * w + l31) * LV + 16 * s2 + 8 * hh); S[kt] = MFMA32(a, bv, S[kt]); }
;             }
;             if (FULL) {
; #pragma unroll
;                 for (int i = 0; i < 16; ++i) Ot[crow(i, hh) * LO + 32 * w + l31] = o[i];
;                 __syncthreads();
	v_mfma_f32_32x32x16_bf16 v[80:95], v[128:131], v[124:127], v[80:95]
	v_mul_f32_e64 v2, v2, v232
	v_mul_f32_e64 v3, v3, v233
	v_mul_f32_e64 v6, v6, v236
	v_mul_f32_e64 v7, v7, v237
	v_mul_f32_e64 v10, v10, v240
	v_mul_f32_e64 v11, v11, v241
	v_pk_mul_f32 v[14:15], v[14:15], v[244:245]
	v_pk_mul_f32 v[12:13], v[12:13], v[242:243]
	v_pk_mul_f32 v[8:9], v[8:9], v[238:239]
	v_pk_mul_f32 v[4:5], v[4:5], v[234:235]
	v_pk_mul_f32 v[0:1], v[0:1], v[230:231]
	ds_read_b128 v[230:233], v208 offset:35840
	ds_read_b128 v[234:237], v208 offset:35872
	ds_read_b128 v[238:241], v32 offset:46080
	ds_read_b128 v[242:245], v32 offset:46112
	s_waitcnt lgkmcnt(0)
	v_mfma_f32_32x32x16_bf16 v[0:15], v[230:233], v[238:241], v[0:15]
	v_add_u32_e32 v32, 0x600, v212
	v_mfma_f32_32x32x16_bf16 v[0:15], v[234:237], v[242:245], v[0:15]
	ds_read_b128 v[230:233], v153 offset:1152
	ds_read_b128 v[234:237], v153 offset:1184
	ds_read_b128 v[246:249], v153 offset:1216
	ds_read_b128 v[250:253], v153 offset:1248
	s_waitcnt lgkmcnt(0)
	v_pk_mul_f32 v[18:19], v[18:19], v[232:233]
	v_pk_mul_f32 v[22:23], v[22:23], v[236:237]
	v_pk_mul_f32 v[20:21], v[20:21], v[234:235]
	v_pk_mul_f32 v[16:17], v[16:17], v[230:231]
	ds_read_b128 v[230:233], v209 offset:35840
	ds_read_b128 v[234:237], v209 offset:35872
	v_pk_mul_f32 v[30:31], v[30:31], v[252:253]
	v_pk_mul_f32 v[26:27], v[26:27], v[248:249]
	v_pk_mul_f32 v[28:29], v[28:29], v[250:251]
	v_pk_mul_f32 v[24:25], v[24:25], v[246:247]
	v_mfma_f32_32x32x16_bf16 v[80:95], v[120:123], v[116:119], v[80:95]
	s_waitcnt lgkmcnt(0)
	v_mfma_f32_32x32x16_bf16 v[16:31], v[230:233], v[238:241], v[16:31]
	v_mfma_f32_32x32x16_bf16 v[16:31], v[234:237], v[242:245], v[16:31]
	ds_read_b128 v[230:233], v153 offset:1280
	ds_read_b128 v[234:237], v153 offset:1312
	ds_read_b128 v[246:249], v153 offset:1344
	ds_read_b128 v[250:253], v153 offset:1376
	s_waitcnt lgkmcnt(0)
	v_pk_mul_f32 v[50:51], v[50:51], v[232:233]
	v_pk_mul_f32 v[54:55], v[54:55], v[236:237]
	v_pk_mul_f32 v[52:53], v[52:53], v[234:235]
	v_pk_mul_f32 v[48:49], v[48:49], v[230:231]
	ds_read_b128 v[230:233], v210 offset:35840
	ds_read_b128 v[234:237], v210 offset:35872
	v_pk_mul_f32 v[62:63], v[62:63], v[252:253]
	v_pk_mul_f32 v[58:59], v[58:59], v[248:249]
	v_pk_mul_f32 v[60:61], v[60:61], v[250:251]
	v_pk_mul_f32 v[56:57], v[56:57], v[246:247]
	s_waitcnt lgkmcnt(0)
	s_nop 0
	v_mfma_f32_32x32x16_bf16 v[48:63], v[230:233], v[238:241], v[48:63]
	v_mfma_f32_32x32x16_bf16 v[48:63], v[234:237], v[242:245], v[48:63]
	ds_read_b128 v[230:233], v153 offset:1408
	ds_read_b128 v[234:237], v153 offset:1440
	ds_read_b128 v[246:249], v153 offset:1472
	ds_read_b128 v[250:253], v153 offset:1504
	s_waitcnt lgkmcnt(0)
	v_pk_mul_f32 v[66:67], v[66:67], v[232:233]
	v_pk_mul_f32 v[70:71], v[70:71], v[236:237]
	v_pk_mul_f32 v[68:69], v[68:69], v[234:235]
	v_pk_mul_f32 v[64:65], v[64:65], v[230:231]
	ds_read_b128 v[230:233], v211 offset:35840
	ds_read_b128 v[234:237], v211 offset:35872
	ds_write2_b32 v213, v80, v81 offset1:132
	ds_write2_b32 v32, v82, v83 offset1:132
	v_add_u32_e32 v32, 0x1200, v212
	ds_write2_b32 v32, v84, v85 offset0:24 offset1:156
	v_add_u32_e32 v32, 0x1600, v212
	ds_write2_b32 v32, v86, v87 offset0:32 offset1:164
	v_add_u32_e32 v32, 0x2200, v212
	ds_write2_b32 v32, v88, v89 offset0:56 offset1:188
	v_add_u32_e32 v32, 0x2600, v212
	ds_write2_b32 v32, v90, v91 offset0:64 offset1:196
	v_add_u32_e32 v32, 0x3200, v212
	ds_write2_b32 v32, v92, v93 offset0:88 offset1:220
	v_add_u32_e32 v32, 0x3600, v212
	ds_write2_b32 v32, v94, v95 offset0:96 offset1:228
	s_waitcnt lgkmcnt(0)
	s_barrier
; DI unsigned pk_bf16(float a, float b) { f32x2_t v = {a, b}; bf16x2_t r = __builtin_convertvector(v, bf16x2_t); return __builtin_bit_cast(unsigned, r); }
; template <bool FULL>
; DI void hgrn_pass(const Params& p, const int j, char* lds) {
;     ...
;         for (int c = 0; c < 8; ++c) {
;             const size_t row0 = rowS + c * 32;
;             float bc[16];
;             {
;                 float run = 0.f;
; #pragma unroll
;                 for (int t = 0; t < 16; ++t) { run += lf[t]; bc[t] = run; }
;                 tot[half * 128 + kk] = run;
;             }
;             __syncthreads();
;             {
;                 const float t0v = tot[kk], t1v = tot[128 + kk];
;                 const float blast = t0v + t1v;
;                 const float add = half ? t0v : 0.f;
;                 if (half == 0) { dvec[kk] = __expf(blast); segsum += blast; }
;     ...
;                 const int t = tid >> 3, sg = tid & 7;
;                 f32x4 ov[4]; float ss = 0.f;
; #pragma unroll
;                 for (int q = 0; q < 4; ++q) { ov[q] = *(const f32x4*)(Ot + t * LO + sg * 16 + 4 * q); ss += ov[q][0] * ov[q][0] + ov[q][1] * ov[q][1] + ov[q][2] * ov[q][2] + ov[q][3] * ov[q][3]; }
;                 ss += shx(ss, 1); ss += shx(ss, 2); ss += shx(ss, 4);
;                 const float rs = rsqrtf(ss * (1.f / 128.f) + EPS);
;                 float gt[16];
; #pragma unroll
;                 for (int e = 0; e < 4; ++e) { gt[2 * e] = __uint_as_float(gg0[e] << 16); gt[2 * e + 1] = __uint_as_float(gg0[e] & 0xffff0000u);
;                     gt[8 + 2 * e] = __uint_as_float(gg1[e] << 16); gt[8 + 2 * e + 1] = __uint_as_float(gg1[e] & 0xffff0000u); }
;                 float res[16];
; #pragma unroll
;                 for (int q = 0; q < 4; ++q) { const f32x4 gn = *(const f32x4*)(ggain + sg * 16 + 4 * q);
; #pragma unroll
;                     for (int e = 0; e < 4; ++e) res[4 * q + e] = ov[q][e] * rs * gn[e] * gt[4 * q + e]; }
;                 u32x4 o0, o1;
; #pragma unroll
;                 for (int e = 0; e < 4; ++e) { o0[e] = pk_bf16(res[2 * e], res[2 * e + 1]); o1[e] = pk_bf16(res[8 + 2 * e], res[8 + 2 * e + 1]); }
;                 bf16_t* dst = MIX + (row0 + t) * DM + h * 128 + sg * 16;
;                 *(u32x4*)dst = o0; *(u32x4*)(dst + 8) = o1;
	ds_read_b128 v[92:95], v155 offset:1536
	ds_read_b128 v[88:91], v155 offset:1552
	ds_read_b128 v[84:87], v155 offset:1568
	ds_read_b128 v[80:83], v155 offset:1584
	v_pk_mul_f32 v[78:79], v[78:79], v[252:253]
	s_waitcnt lgkmcnt(0)
	v_mov_b32_e32 v118, v93
	v_mov_b32_e32 v119, v89
	v_mov_b32_e32 v116, v92
	v_mov_b32_e32 v117, v88
	v_pk_mul_f32 v[118:119], v[118:119], v[118:119]
	v_mov_b32_e32 v120, v85
	v_pk_fma_f32 v[116:117], v[116:117], v[116:117], v[118:119]
	v_mov_b32_e32 v118, v94
	v_mov_b32_e32 v119, v90
	v_pk_fma_f32 v[116:117], v[118:119], v[118:119], v[116:117]
	v_mov_b32_e32 v118, v95
	v_mov_b32_e32 v119, v91
	v_mov_b32_e32 v121, v81
	v_pk_fma_f32 v[116:117], v[118:119], v[118:119], v[116:117]
	v_mov_b32_e32 v118, v84
	v_mov_b32_e32 v119, v80
	v_pk_mul_f32 v[120:121], v[120:121], v[120:121]
	v_add_f32_e32 v32, v116, v117
	v_pk_fma_f32 v[118:119], v[118:119], v[118:119], v[120:121]
	v_mov_b32_e32 v120, v86
	v_mov_b32_e32 v121, v82
	v_pk_fma_f32 v[118:119], v[120:121], v[120:121], v[118:119]
	v_mov_b32_e32 v120, v87
	v_mov_b32_e32 v121, v83
	v_pk_fma_f32 v[118:119], v[120:121], v[120:121], v[118:119]
	v_mbcnt_lo_u32_b32 v116, -1, 0
	v_mbcnt_hi_u32_b32 v116, -1, v116
	v_pk_mul_f32 v[74:75], v[74:75], v[248:249]
	v_add_f32_e32 v32, v32, v118
	v_lshlrev_b32_e32 v116, 2, v116
	v_add_f32_e32 v32, v32, v119
	v_bitop3_b32 v116, v116, 4, v199 bitop3:0x6c
	ds_bpermute_b32 v116, v116, v32
	v_pk_mul_f32 v[76:77], v[76:77], v[250:251]
	v_pk_mul_f32 v[72:73], v[72:73], v[246:247]
	s_waitcnt lgkmcnt(0)
	v_add_f32_e32 v32, v32, v116
	v_mbcnt_lo_u32_b32 v116, -1, 0
	v_mbcnt_hi_u32_b32 v116, -1, v116
	v_mfma_f32_32x32x16_bf16 v[64:79], v[230:233], v[238:241], v[64:79]
	v_lshlrev_b32_e32 v116, 2, v116
	v_bitop3_b32 v116, v116, 8, v199 bitop3:0x6c
	ds_bpermute_b32 v116, v116, v32
	s_waitcnt vmcnt(0)
	v_lshlrev_b32_e32 v230, 16, v112
	v_and_b32_e32 v231, 0xffff0000, v112
	v_lshlrev_b32_e32 v112, 16, v113
	v_and_b32_e32 v113, 0xffff0000, v113
	s_waitcnt lgkmcnt(0)
	v_add_f32_e32 v32, v32, v116
	v_mbcnt_lo_u32_b32 v116, -1, 0
	v_mbcnt_hi_u32_b32 v116, -1, v116
	v_mfma_f32_32x32x16_bf16 v[64:79], v[234:237], v[242:245], v[64:79]
	v_lshlrev_b32_e32 v116, 2, v116
	v_bitop3_b32 v116, v116, 16, v199 bitop3:0x6c
	ds_bpermute_b32 v116, v116, v32
	s_waitcnt lgkmcnt(0)
	v_add_f32_e32 v32, v32, v116
	v_fmamk_f32 v32, v32, 0x3c000000, v197
	v_cmp_gt_f32_e32 vcc, s79, v32
	v_mul_f32_e32 v116, 0x4b800000, v32
	s_nop 0
	v_cndmask_b32_e32 v32, v32, v116, vcc
	v_rsq_f32_e32 v32, v32
	s_nop 0
	v_mul_f32_e32 v116, 0x45800000, v32
	v_cndmask_b32_e32 v32, v32, v116, vcc
	global_load_dwordx4 v[116:119], v[140:141], off offset:48
	global_load_dwordx4 v[120:123], v[140:141], off offset:32
	global_load_dwordx4 v[124:127], v[140:141], off offset:16
	global_load_dwordx4 v[128:131], v[140:141], off
	v_pk_mul_f32 v[94:95], v[94:95], v[32:33] op_sel_hi:[1,0]
	v_pk_mul_f32 v[88:89], v[88:89], v[32:33] op_sel_hi:[1,0]
	v_pk_mul_f32 v[90:91], v[90:91], v[32:33] op_sel_hi:[1,0]
	v_pk_mul_f32 v[86:87], v[86:87], v[32:33] op_sel_hi:[1,0]
	v_pk_mul_f32 v[80:81], v[80:81], v[32:33] op_sel_hi:[1,0]
	v_pk_mul_f32 v[82:83], v[82:83], v[32:33] op_sel_hi:[1,0]
	v_pk_mul_f32 v[92:93], v[92:93], v[32:33] op_sel_hi:[1,0]
	v_pk_mul_f32 v[84:85], v[84:85], v[32:33] op_sel_hi:[1,0]
	s_waitcnt vmcnt(3)
	v_pk_mul_f32 v[80:81], v[116:117], v[80:81]
	s_waitcnt vmcnt(2)
	v_pk_mul_f32 v[86:87], v[122:123], v[86:87]
	s_waitcnt vmcnt(1)
	v_pk_mul_f32 v[88:89], v[124:125], v[88:89]
	s_waitcnt vmcnt(0)
	v_pk_mul_f32 v[94:95], v[130:131], v[94:95]
	v_pk_mul_f32 v[90:91], v[126:127], v[90:91]
	v_pk_mul_f32 v[94:95], v[94:95], v[112:113]
	v_lshlrev_b32_e32 v112, 16, v114
	v_and_b32_e32 v113, 0xffff0000, v114
	v_pk_mul_f32 v[88:89], v[88:89], v[112:113]
	v_lshlrev_b32_e32 v112, 16, v115
	v_and_b32_e32 v113, 0xffff0000, v115
	v_pk_mul_f32 v[90:91], v[90:91], v[112:113]
	v_lshlrev_b32_e32 v112, 16, v108
	v_and_b32_e32 v113, 0xffff0000, v108
	v_lshlrev_b32_e32 v108, 16, v109
	v_and_b32_e32 v109, 0xffff0000, v109
	v_pk_mul_f32 v[86:87], v[86:87], v[108:109]
	v_lshlrev_b32_e32 v108, 16, v110
	v_and_b32_e32 v109, 0xffff0000, v110
	v_pk_mul_f32 v[108:109], v[80:81], v[108:109]
	v_lshlrev_b32_e32 v80, 16, v111
	v_and_b32_e32 v81, 0xffff0000, v111
	v_pk_mul_f32 v[82:83], v[118:119], v[82:83]
	v_pk_mul_f32 v[92:93], v[128:129], v[92:93]
	v_pk_mul_f32 v[110:111], v[82:83], v[80:81]
	v_cvt_pk_bf16_f32 v82, v88, v89
	v_lshl_add_u64 v[88:89], s[68:69], 0, v[180:181]
	v_pk_mul_f32 v[92:93], v[92:93], v[230:231]
	v_pk_mul_f32 v[84:85], v[120:121], v[84:85]
	v_add_co_u32_e32 v88, vcc, s64, v88
	s_mov_b64 s[64:65], 0x10000
	v_pk_mul_f32 v[84:85], v[84:85], v[112:113]
	v_cvt_pk_bf16_f32 v80, v92, v93
	v_cvt_pk_bf16_f32 v81, v94, v95
	v_cvt_pk_bf16_f32 v83, v90, v91
	v_addc_co_u32_e32 v89, vcc, 0, v89, vcc
	v_lshl_add_u64 v[180:181], v[180:181], 0, s[64:65]
	v_cvt_pk_bf16_f32 v84, v84, v85
	v_cvt_pk_bf16_f32 v85, v86, v87
	v_cvt_pk_bf16_f32 v86, v108, v109
	v_cvt_pk_bf16_f32 v87, v110, v111
	global_store_dwordx4 v[88:89], v[80:83], off
	global_store_dwordx4 v[88:89], v[84:87], off offset:16
	s_cbranch_scc1 .LBB0_183
.LBB0_190:
	s_waitcnt vmcnt(2) lgkmcnt(0)
	v_add_f32_e32 v93, 0, v214
	v_add_f32_e32 v94, v93, v215
	v_add_f32_e32 v91, v94, v216
	v_add_f32_e32 v92, v91, v217
	v_add_f32_e32 v89, v92, v218
	v_add_f32_e32 v90, v89, v219
	v_add_f32_e32 v87, v90, v220
	v_add_f32_e32 v88, v87, v221
	v_add_f32_e32 v85, v88, v222
	v_add_f32_e32 v86, v85, v223
	v_add_f32_e32 v83, v86, v224
	v_add_f32_e32 v84, v83, v225
	v_add_f32_e32 v81, v84, v226
	v_add_f32_e32 v82, v81, v227
	v_add_f32_e32 v32, v82, v228
	v_add_f32_e32 v80, v32, v229
	ds_write_b32 v139, v80
	s_waitcnt lgkmcnt(0)
	s_barrier
	ds_read_b32 v95, v143
	s_and_saveexec_b64 s[64:65], s[38:39]
	s_cbranch_execz .LBB0_192
	ds_read_b32 v108, v143 offset:512
	s_waitcnt lgkmcnt(0)
	v_add_f32_e32 v108, v95, v108
	v_mul_f32_e32 v108, 0x3fb8aa3b, v108
	v_exp_f32_e32 v108, v108
	ds_write_b32 v143, v108 offset:1024
